# m1+m2, no per-segment setprio, static s_setprio 1 for waves 4-7
# speedup vs baseline: 1.0115x; 1.0029x over previous
; #define LAS __attribute__((address_space(3)))
; __device__ __forceinline__ unsigned xb_add(unsigned* p, unsigned v) { return __hip_atomic_fetch_add(p, v, __ATOMIC_RELAXED, __HIP_MEMORY_SCOPE_AGENT); }
; __device__ __forceinline__ unsigned xb_xcc_id() { return (unsigned)__builtin_amdgcn_s_getreg((3 << 11) | 20) & 0xFu; }
; __device__ __forceinline__ XcdBarrier xcd_barrier_post(unsigned* bar, volatile LAS unsigned* st) {
;     XcdBarrier b; b.bar = bar; b.x = xb_xcc_id(); b.st = st;
;     if (threadIdx.x == 0) (void)xb_add(&bar[XB_XCNT(b.x)], 1u);
;     return b;
; __global__ void __launch_bounds__(512, 2) mega(Args a) {
;     extern __shared__ __attribute__((aligned(16))) unsigned char lds_raw[];
;     LAS unsigned char* lds = (LAS unsigned char*)lds_raw;
;     if (threadIdx.x < 4) ((LAS unsigned*)(lds + LDS_ST))[threadIdx.x] = 0u;
;     __syncthreads();
;     (void)xcd_barrier_post((unsigned*)(a.ws + WS_BAR), (volatile LAS unsigned*)(lds + LDS_ST));
_Z4mega4Args:
	v_and_b32_e32 v222, 0x3ff, v0
	s_mov_b32 s91, s2
	s_mov_b64 s[92:93], s[0:1]
	s_nop 0
	v_readfirstlane_b32 s4, v222
	s_nop 3
	s_lshr_b32 s4, s4, 6
	s_cmp_ge_u32 s4, 4
	s_cbranch_scc0 .Lprio_done
	s_setprio 1
.Lprio_done:
	v_cmp_gt_u32_e32 vcc, 4, v222
	s_and_saveexec_b64 s[4:5], vcc
	v_lshl_add_u32 v1, v222, 2, 0
	v_add_u32_e32 v1, 0x22ff0, v1
	v_mov_b32_e32 v2, 0
	ds_write_b32 v1, v2
	s_or_b64 exec, exec, s[4:5]
	s_load_dword s3, s[92:93], 0xc0
	s_waitcnt lgkmcnt(0)
	s_barrier
	s_getreg_b32 s0, hwreg(HW_REG_XCC_ID, 0, 4)
	s_mov_b32 s27, 0
	v_cmp_eq_u32_e64 s[94:95], 0, v222
	s_and_saveexec_b64 s[4:5], s[94:95]
	s_cbranch_execz .LBB0_5
	s_mov_b64 s[6:7], exec
	v_mbcnt_lo_u32_b32 v1, s6, 0
	v_mbcnt_hi_u32_b32 v1, s7, v1
	v_cmp_eq_u32_e32 vcc, 0, v1
	s_and_b64 s[8:9], exec, vcc
	s_mov_b64 exec, s[8:9]
	s_cbranch_execz .LBB0_5
	s_load_dwordx2 s[8:9], s[92:93], 0xb8
	s_lshl_b32 s0, s0, 8
	s_and_b32 s0, s0, 0xf00
	v_mov_b32_e32 v1, 0x80000
	s_waitcnt lgkmcnt(0)
	s_add_u32 s0, s8, s0
	s_addc_u32 s1, s9, 0
	s_bcnt1_i32_b64 s2, s[6:7]
	v_mov_b32_e32 v2, s2
	global_atomic_add v1, v2, s[0:1] offset:1024
